# B/C ORD1 loops: same unneeded 2-wait-state pad before the row-sum swap removed
# baseline (speedup 1.0000x reference)
; template <bool EXP1 = true>
; __device__ __forceinline__ void finishSM(f32x16& p0, f32x16& p1, float alpha, float& l_reg, bf16x8& pa0, bf16x8& pa1, bf16x8& pa2, bf16x8& pa3) {
;   if constexpr (EXP1) {
; #pragma unroll
;   for (int r = 0; r < 16; ++r) p1[r] = __builtin_amdgcn_exp2f(p1[r]);
;   }
;   float sm_[4] = {p0[0], p0[1], p0[2], p0[3]};
; #pragma unroll
;   for (int r = 4; r < 16; ++r) sm_[r & 3] += p0[r];
; #pragma unroll
;   for (int r = 0; r < 16; ++r) sm_[r & 3] += p1[r];
;   float ps = (sm_[0] + sm_[1]) + (sm_[2] + sm_[3]);
;   { auto rr = __builtin_amdgcn_permlane32_swap(__float_as_uint(ps), __float_as_uint(ps), false, false);
;     ps = __uint_as_float(rr[0]) + __uint_as_float(rr[1]); }
;   l_reg = l_reg * alpha + ps;
;     ...
;   PK4(p0, 0, pa0); PK4(p0, 8, pa1); PK4(p1, 0, pa2); PK4(p1, 8, pa3);
;     ...
; }
.LBB0_360:
	v_exp_f32_e32 v66, v66
	v_exp_f32_e32 v67, v67
	v_exp_f32_e32 v68, v68
	v_exp_f32_e32 v69, v69
	v_exp_f32_e32 v70, v70
	v_exp_f32_e32 v71, v71
	v_exp_f32_e32 v72, v72
	v_exp_f32_e32 v73, v73
	v_add_f32_e32 v98, v148, v146
	v_add_f32_e32 v99, v159, v161
	v_add_f32_e32 v100, v149, v147
	v_add_f32_e32 v101, v158, v160
	v_exp_f32_e32 v74, v74
	v_exp_f32_e32 v75, v75
	v_exp_f32_e32 v76, v76
	v_exp_f32_e32 v77, v77
	v_add_f32_e32 v98, v150, v98
	v_add_f32_e32 v99, v157, v99
	v_add_f32_e32 v100, v151, v100
	v_add_f32_e32 v101, v156, v101
	v_exp_f32_e32 v78, v78
	v_exp_f32_e32 v79, v79
	v_exp_f32_e32 v80, v80
	v_exp_f32_e32 v81, v81
	v_add_f32_e32 v98, v152, v98
	v_add_f32_e32 v99, v155, v99
	v_add_f32_e32 v100, v153, v100
	v_add_f32_e32 v101, v154, v101
	v_add_f32_e32 v98, v66, v98
	v_add_f32_e32 v99, v67, v99
	v_add_f32_e32 v100, v68, v100
	v_add_f32_e32 v101, v69, v101
	v_add_f32_e32 v98, v70, v98
	v_add_f32_e32 v99, v71, v99
	v_add_f32_e32 v100, v72, v100
	v_add_f32_e32 v101, v73, v101
	v_add_f32_e32 v98, v74, v98
	v_add_f32_e32 v99, v75, v99
	v_add_f32_e32 v100, v76, v100
	v_add_f32_e32 v101, v77, v101
	v_add_f32_e32 v98, v78, v98
	v_add_f32_e32 v99, v79, v99
	v_add_f32_e32 v100, v80, v100
	v_add_f32_e32 v101, v81, v101
	v_add_f32_e32 v98, v98, v99
	v_add_f32_e32 v99, v100, v101
	v_add_f32_e32 v224, v98, v99
	v_mov_b32_e32 v225, v224
	v_cvt_pk_bf16_f32 v146, v146, v161
	v_cvt_pk_bf16_f32 v147, v147, v160
	v_cvt_pk_bf16_f32 v148, v148, v159
	v_cvt_pk_bf16_f32 v149, v149, v158
	v_cvt_pk_bf16_f32 v150, v150, v157
	v_cvt_pk_bf16_f32 v151, v151, v156
	v_cvt_pk_bf16_f32 v152, v152, v155
	v_cvt_pk_bf16_f32 v153, v153, v154
	v_cvt_pk_bf16_f32 v158, v66, v67
	v_cvt_pk_bf16_f32 v159, v68, v69
	v_cvt_pk_bf16_f32 v160, v70, v71
	v_cvt_pk_bf16_f32 v161, v72, v73
	v_cvt_pk_bf16_f32 v154, v74, v75
	v_cvt_pk_bf16_f32 v155, v76, v77
	v_cvt_pk_bf16_f32 v156, v78, v79
	v_cvt_pk_bf16_f32 v157, v80, v81
	v_permlane32_swap_b32_e32 v224, v225
	v_cmp_neq_f32_e64 s[6:7], v229, -v226
	s_cmp_eq_u64 s[6:7], 0
	s_cselect_b64 s[6:7], -1, 0
	s_cbranch_scc0 .Lmy_negm_slow_0
	v_mov_b64_e32 v[66:67], v[82:83]
	v_mov_b64_e32 v[68:69], v[84:85]
	v_mov_b64_e32 v[70:71], v[86:87]
	v_mov_b64_e32 v[72:73], v[88:89]
	v_mov_b64_e32 v[74:75], v[90:91]
	v_mov_b64_e32 v[76:77], v[92:93]
	v_mov_b64_e32 v[78:79], v[94:95]
	v_mov_b64_e32 v[80:81], v[96:97]

; template <bool FIRST>
; __device__ __forceinline__ void partialSM(f32x16& p0, f32x16& p1, float& mC, float& alpha) {
;     ...
;   for (int r = 0; r < 16; ++r) p0[r] = __builtin_amdgcn_exp2f(p0[r]);
; }
; template <bool EXP1 = true>
; __device__ __forceinline__ void finishSM(f32x16& p0, f32x16& p1, float alpha, float& l_reg, bf16x8& pa0, bf16x8& pa1, bf16x8& pa2, bf16x8& pa3) {
;   if constexpr (EXP1) {
; #pragma unroll
;   for (int r = 0; r < 16; ++r) p1[r] = __builtin_amdgcn_exp2f(p1[r]);
;   }
;   float sm_[4] = {p0[0], p0[1], p0[2], p0[3]};
; #pragma unroll
;   for (int r = 4; r < 16; ++r) sm_[r & 3] += p0[r];
; #pragma unroll
;   for (int r = 0; r < 16; ++r) sm_[r & 3] += p1[r];
;   float ps = (sm_[0] + sm_[1]) + (sm_[2] + sm_[3]);
;   { auto rr = __builtin_amdgcn_permlane32_swap(__float_as_uint(ps), __float_as_uint(ps), false, false);
;     ps = __uint_as_float(rr[0]) + __uint_as_float(rr[1]); }
;   l_reg = l_reg * alpha + ps;
;     ...
;   PK4(p0, 0, pa0); PK4(p0, 8, pa1); PK4(p1, 0, pa2); PK4(p1, 8, pa3);
;     ...
; }
.LBB0_366:
	v_exp_f32_e32 v146, v98
	v_exp_f32_e32 v153, v99
	v_exp_f32_e32 v147, v100
	v_exp_f32_e32 v152, v101
	v_exp_f32_e32 v148, v102
	v_exp_f32_e32 v151, v103
	v_exp_f32_e32 v149, v104
	v_exp_f32_e32 v150, v105
	v_exp_f32_e32 v103, v106
	v_exp_f32_e32 v105, v107
	v_exp_f32_e32 v101, v108
	v_exp_f32_e32 v104, v109
	v_exp_f32_e32 v99, v110
	v_exp_f32_e32 v102, v111
	v_exp_f32_e32 v98, v112
	v_exp_f32_e32 v100, v113
	v_xor_b32_e32 v106, 0x80000000, v226
	v_exp_f32_e32 v82, v82
	v_exp_f32_e32 v83, v83
	v_exp_f32_e32 v84, v84
	v_exp_f32_e32 v85, v85
	v_cndmask_b32_e64 v229, v106, v229, s[6:7]
	v_exp_f32_e32 v86, v86
	v_exp_f32_e32 v87, v87
	v_exp_f32_e32 v88, v88
	v_exp_f32_e32 v89, v89
	v_add_f32_e32 v106, v148, v146
	v_add_f32_e32 v107, v151, v153
	v_add_f32_e32 v108, v149, v147
	v_add_f32_e32 v109, v150, v152
	v_exp_f32_e32 v90, v90
	v_exp_f32_e32 v91, v91
	v_exp_f32_e32 v92, v92
	v_exp_f32_e32 v93, v93
	v_add_f32_e32 v106, v103, v106
	v_add_f32_e32 v107, v105, v107
	v_add_f32_e32 v108, v101, v108
	v_add_f32_e32 v109, v104, v109
	v_exp_f32_e32 v94, v94
	v_exp_f32_e32 v95, v95
	v_exp_f32_e32 v96, v96
	v_exp_f32_e32 v97, v97
	v_add_f32_e32 v106, v99, v106
	v_add_f32_e32 v107, v102, v107
	v_add_f32_e32 v108, v98, v108
	v_add_f32_e32 v109, v100, v109
	v_add_f32_e32 v106, v82, v106
	v_add_f32_e32 v107, v107, v83
	v_add_f32_e32 v108, v108, v84
	v_add_f32_e32 v109, v109, v85
	v_add_f32_e32 v106, v86, v106
	v_add_f32_e32 v107, v87, v107
	v_add_f32_e32 v108, v88, v108
	v_add_f32_e32 v109, v89, v109
	v_add_f32_e32 v106, v90, v106
	v_add_f32_e32 v107, v91, v107
	v_add_f32_e32 v108, v92, v108
	v_add_f32_e32 v109, v93, v109
	v_add_f32_e32 v106, v94, v106
	v_add_f32_e32 v107, v95, v107
	v_add_f32_e32 v108, v96, v108
	v_add_f32_e32 v109, v97, v109
	v_add_f32_e32 v106, v106, v107
	v_add_f32_e32 v107, v108, v109
	v_add_f32_e32 v230, v106, v107
	s_waitcnt lgkmcnt(0)
	s_barrier
	v_mov_b32_e32 v231, v230
	v_cvt_pk_bf16_f32 v146, v146, v153
	v_cvt_pk_bf16_f32 v147, v147, v152
	v_cvt_pk_bf16_f32 v148, v148, v151
	v_cvt_pk_bf16_f32 v149, v149, v150
	v_cvt_pk_bf16_f32 v150, v103, v105
	v_cvt_pk_bf16_f32 v151, v101, v104
	v_cvt_pk_bf16_f32 v152, v99, v102
	v_cvt_pk_bf16_f32 v153, v98, v100
	v_cvt_pk_bf16_f32 v158, v82, v83
	v_cvt_pk_bf16_f32 v159, v84, v85
	v_cvt_pk_bf16_f32 v160, v86, v87
	v_cvt_pk_bf16_f32 v161, v88, v89
	v_cvt_pk_bf16_f32 v154, v90, v91
	v_cvt_pk_bf16_f32 v155, v92, v93
	v_cvt_pk_bf16_f32 v156, v94, v95
	v_cvt_pk_bf16_f32 v157, v96, v97
	v_permlane32_swap_b32_e32 v230, v231
	v_cmp_neq_f32_e64 s[6:7], v229, -v228
	s_cmp_eq_u64 s[6:7], 0
	s_cselect_b64 s[6:7], -1, 0
	s_cbranch_scc0 .Lmy_negm_slow_1
	v_mov_b64_e32 v[82:83], v[66:67]
	v_mov_b64_e32 v[84:85], v[68:69]
	v_mov_b64_e32 v[86:87], v[70:71]
	v_mov_b64_e32 v[88:89], v[72:73]
	v_mov_b64_e32 v[90:91], v[74:75]
	v_mov_b64_e32 v[92:93], v[76:77]
	v_mov_b64_e32 v[94:95], v[78:79]
	v_mov_b64_e32 v[96:97], v[80:81]

; template <bool EXP1 = true>
; __device__ __forceinline__ void finishSM(f32x16& p0, f32x16& p1, float alpha, float& l_reg, bf16x8& pa0, bf16x8& pa1, bf16x8& pa2, bf16x8& pa3) {
;   if constexpr (EXP1) {
; #pragma unroll
;   for (int r = 0; r < 16; ++r) p1[r] = __builtin_amdgcn_exp2f(p1[r]);
;   }
;   float sm_[4] = {p0[0], p0[1], p0[2], p0[3]};
; #pragma unroll
;   for (int r = 4; r < 16; ++r) sm_[r & 3] += p0[r];
; #pragma unroll
;   for (int r = 0; r < 16; ++r) sm_[r & 3] += p1[r];
;   float ps = (sm_[0] + sm_[1]) + (sm_[2] + sm_[3]);
;   { auto rr = __builtin_amdgcn_permlane32_swap(__float_as_uint(ps), __float_as_uint(ps), false, false);
;     ps = __uint_as_float(rr[0]) + __uint_as_float(rr[1]); }
;   l_reg = l_reg * alpha + ps;
;     ...
;   PK4(p0, 0, pa0); PK4(p0, 8, pa1); PK4(p1, 0, pa2); PK4(p1, 8, pa3);
;     ...
; }
.LBB0_421:
	v_exp_f32_e32 v66, v66
	v_exp_f32_e32 v67, v67
	v_exp_f32_e32 v68, v68
	v_exp_f32_e32 v69, v69
	v_exp_f32_e32 v70, v70
	v_exp_f32_e32 v71, v71
	v_exp_f32_e32 v72, v72
	v_exp_f32_e32 v73, v73
	v_add_f32_e32 v98, v148, v146
	v_add_f32_e32 v99, v159, v161
	v_add_f32_e32 v100, v149, v147
	v_add_f32_e32 v101, v158, v160
	v_exp_f32_e32 v74, v74
	v_exp_f32_e32 v75, v75
	v_exp_f32_e32 v76, v76
	v_exp_f32_e32 v77, v77
	v_add_f32_e32 v98, v150, v98
	v_add_f32_e32 v99, v157, v99
	v_add_f32_e32 v100, v151, v100
	v_add_f32_e32 v101, v156, v101
	v_exp_f32_e32 v78, v78
	v_exp_f32_e32 v79, v79
	v_exp_f32_e32 v80, v80
	v_exp_f32_e32 v81, v81
	v_add_f32_e32 v98, v152, v98
	v_add_f32_e32 v99, v155, v99
	v_add_f32_e32 v100, v153, v100
	v_add_f32_e32 v101, v154, v101
	v_add_f32_e32 v98, v66, v98
	v_add_f32_e32 v99, v67, v99
	v_add_f32_e32 v100, v68, v100
	v_add_f32_e32 v101, v69, v101
	v_add_f32_e32 v98, v70, v98
	v_add_f32_e32 v99, v71, v99
	v_add_f32_e32 v100, v72, v100
	v_add_f32_e32 v101, v73, v101
	v_add_f32_e32 v98, v74, v98
	v_add_f32_e32 v99, v75, v99
	v_add_f32_e32 v100, v76, v100
	v_add_f32_e32 v101, v77, v101
	v_add_f32_e32 v98, v78, v98
	v_add_f32_e32 v99, v79, v99
	v_add_f32_e32 v100, v80, v100
	v_add_f32_e32 v101, v81, v101
	v_add_f32_e32 v98, v98, v99
	v_add_f32_e32 v99, v100, v101
	v_add_f32_e32 v228, v98, v99
	v_mov_b32_e32 v229, v228
	v_cvt_pk_bf16_f32 v146, v146, v161
	v_cvt_pk_bf16_f32 v147, v147, v160
	v_cvt_pk_bf16_f32 v148, v148, v159
	v_cvt_pk_bf16_f32 v149, v149, v158
	v_cvt_pk_bf16_f32 v150, v150, v157
	v_cvt_pk_bf16_f32 v151, v151, v156
	v_cvt_pk_bf16_f32 v152, v152, v155
	v_cvt_pk_bf16_f32 v153, v153, v154
	v_cvt_pk_bf16_f32 v158, v66, v67
	v_cvt_pk_bf16_f32 v159, v68, v69
	v_cvt_pk_bf16_f32 v160, v70, v71
	v_cvt_pk_bf16_f32 v161, v72, v73
	v_cvt_pk_bf16_f32 v154, v74, v75
	v_cvt_pk_bf16_f32 v155, v76, v77
	v_cvt_pk_bf16_f32 v156, v78, v79
	v_cvt_pk_bf16_f32 v157, v80, v81
	v_permlane32_swap_b32_e32 v228, v229
	v_cmp_neq_f32_e64 s[6:7], v232, -v227
	s_cmp_eq_u64 s[6:7], 0
	s_cselect_b64 s[6:7], -1, 0
	s_cbranch_scc0 .Lmy_negm_slow_2
	v_mov_b64_e32 v[66:67], v[82:83]
	v_mov_b64_e32 v[68:69], v[84:85]
	v_mov_b64_e32 v[70:71], v[86:87]
	v_mov_b64_e32 v[72:73], v[88:89]
	v_mov_b64_e32 v[74:75], v[90:91]
	v_mov_b64_e32 v[76:77], v[92:93]
	v_mov_b64_e32 v[78:79], v[94:95]
	v_mov_b64_e32 v[80:81], v[96:97]

; template <bool FIRST>
; __device__ __forceinline__ void partialSM(f32x16& p0, f32x16& p1, float& mC, float& alpha) {
;     ...
;   for (int r = 0; r < 16; ++r) p0[r] = __builtin_amdgcn_exp2f(p0[r]);
; }
; template <bool EXP1 = true>
; __device__ __forceinline__ void finishSM(f32x16& p0, f32x16& p1, float alpha, float& l_reg, bf16x8& pa0, bf16x8& pa1, bf16x8& pa2, bf16x8& pa3) {
;   if constexpr (EXP1) {
; #pragma unroll
;   for (int r = 0; r < 16; ++r) p1[r] = __builtin_amdgcn_exp2f(p1[r]);
;   }
;   float sm_[4] = {p0[0], p0[1], p0[2], p0[3]};
; #pragma unroll
;   for (int r = 4; r < 16; ++r) sm_[r & 3] += p0[r];
; #pragma unroll
;   for (int r = 0; r < 16; ++r) sm_[r & 3] += p1[r];
;   float ps = (sm_[0] + sm_[1]) + (sm_[2] + sm_[3]);
;   { auto rr = __builtin_amdgcn_permlane32_swap(__float_as_uint(ps), __float_as_uint(ps), false, false);
;     ps = __uint_as_float(rr[0]) + __uint_as_float(rr[1]); }
;   l_reg = l_reg * alpha + ps;
;     ...
;   PK4(p0, 0, pa0); PK4(p0, 8, pa1); PK4(p1, 0, pa2); PK4(p1, 8, pa3);
;     ...
; }
.LBB0_427:
	v_exp_f32_e32 v146, v98
	v_exp_f32_e32 v153, v99
	v_exp_f32_e32 v147, v100
	v_exp_f32_e32 v152, v101
	v_exp_f32_e32 v148, v102
	v_exp_f32_e32 v151, v103
	v_exp_f32_e32 v149, v104
	v_exp_f32_e32 v150, v105
	v_exp_f32_e32 v103, v106
	v_exp_f32_e32 v105, v107
	v_exp_f32_e32 v101, v108
	v_exp_f32_e32 v104, v109
	v_exp_f32_e32 v99, v110
	v_exp_f32_e32 v102, v111
	v_exp_f32_e32 v98, v112
	v_exp_f32_e32 v100, v113
	v_xor_b32_e32 v106, 0x80000000, v227
	v_exp_f32_e32 v82, v82
	v_exp_f32_e32 v83, v83
	v_exp_f32_e32 v84, v84
	v_exp_f32_e32 v85, v85
	v_cndmask_b32_e64 v232, v106, v232, s[6:7]
	v_exp_f32_e32 v86, v86
	v_exp_f32_e32 v87, v87
	v_exp_f32_e32 v88, v88
	v_exp_f32_e32 v89, v89
	v_add_f32_e32 v106, v148, v146
	v_add_f32_e32 v107, v151, v153
	v_add_f32_e32 v108, v149, v147
	v_add_f32_e32 v109, v150, v152
	v_exp_f32_e32 v90, v90
	v_exp_f32_e32 v91, v91
	v_exp_f32_e32 v92, v92
	v_exp_f32_e32 v93, v93
	v_add_f32_e32 v106, v103, v106
	v_add_f32_e32 v107, v105, v107
	v_add_f32_e32 v108, v101, v108
	v_add_f32_e32 v109, v104, v109
	v_exp_f32_e32 v94, v94
	v_exp_f32_e32 v95, v95
	v_exp_f32_e32 v96, v96
	v_exp_f32_e32 v97, v97
	v_add_f32_e32 v106, v99, v106
	v_add_f32_e32 v107, v102, v107
	v_add_f32_e32 v108, v98, v108
	v_add_f32_e32 v109, v100, v109
	v_add_f32_e32 v106, v82, v106
	v_add_f32_e32 v107, v107, v83
	v_add_f32_e32 v108, v108, v84
	v_add_f32_e32 v109, v109, v85
	v_add_f32_e32 v106, v86, v106
	v_add_f32_e32 v107, v87, v107
	v_add_f32_e32 v108, v88, v108
	v_add_f32_e32 v109, v89, v109
	v_add_f32_e32 v106, v90, v106
	v_add_f32_e32 v107, v91, v107
	v_add_f32_e32 v108, v92, v108
	v_add_f32_e32 v109, v93, v109
	v_add_f32_e32 v106, v94, v106
	v_add_f32_e32 v107, v95, v107
	v_add_f32_e32 v108, v96, v108
	v_add_f32_e32 v109, v97, v109
	v_add_f32_e32 v106, v106, v107
	v_add_f32_e32 v107, v108, v109
	v_add_f32_e32 v233, v106, v107
	s_waitcnt lgkmcnt(0)
	s_barrier
	v_mov_b32_e32 v234, v233
	v_cvt_pk_bf16_f32 v146, v146, v153
	v_cvt_pk_bf16_f32 v147, v147, v152
	v_cvt_pk_bf16_f32 v148, v148, v151
	v_cvt_pk_bf16_f32 v149, v149, v150
	v_cvt_pk_bf16_f32 v150, v103, v105
	v_cvt_pk_bf16_f32 v151, v101, v104
	v_cvt_pk_bf16_f32 v152, v99, v102
	v_cvt_pk_bf16_f32 v153, v98, v100
	v_cvt_pk_bf16_f32 v158, v82, v83
	v_cvt_pk_bf16_f32 v159, v84, v85
	v_cvt_pk_bf16_f32 v160, v86, v87
	v_cvt_pk_bf16_f32 v161, v88, v89
	v_cvt_pk_bf16_f32 v154, v90, v91
	v_cvt_pk_bf16_f32 v155, v92, v93
	v_cvt_pk_bf16_f32 v156, v94, v95
	v_cvt_pk_bf16_f32 v157, v96, v97
	v_permlane32_swap_b32_e32 v233, v234
	v_cmp_neq_f32_e64 s[6:7], v232, -v231
	s_cmp_eq_u64 s[6:7], 0
	s_cselect_b64 s[6:7], -1, 0
	s_cbranch_scc0 .Lmy_negm_slow_3
	v_mov_b64_e32 v[82:83], v[66:67]
	v_mov_b64_e32 v[84:85], v[68:69]
	v_mov_b64_e32 v[86:87], v[70:71]
	v_mov_b64_e32 v[88:89], v[72:73]
	v_mov_b64_e32 v[90:91], v[74:75]
	v_mov_b64_e32 v[92:93], v[76:77]
	v_mov_b64_e32 v[94:95], v[78:79]
	v_mov_b64_e32 v[96:97], v[80:81]
